# attention item prologue waits only for the K(0) DMA (vmcnt 9) before the first score tile; remaining ring tiles land under the loop-top wait
# baseline (speedup 1.0000x reference)
; DI int tidx() { int t = threadIdx.x; asm volatile("" : "+v"(t)); return t; }
; DI void attn_item(const Params& p, int L, int b, int h, int qb, float lam, char* lds) {
;   const int tid = tidx(), lane = tid & 63, wave = __builtin_amdgcn_readfirstlane(tid >> 6);
;   const int lq = lane & 31, hi = lane >> 5, rg = wave & 3, m = wave >> 2;
;   bf16_t* qg = (bf16_t*)(p.ws + OFF_Q);
;   const unsigned char* kg8 = (const unsigned char*)(p.ws + OFF_K) + ((size_t)b * L) * 1024 + h * 128;
;   const unsigned char* qg8 = (const unsigned char*)(p.ws + OFF_K) + OFF_Q8;
;   const bf16_t* vg = (const bf16_t*)(p.ws + OFF_V) + (size_t)b * L * 1024 + h * 128;
;   const size_t tok0 = (size_t)b * L + (size_t)qb * 128;
;   v8i_t qf8;
;   {
;     const uint4* qp = (const uint4*)(qg8 + (tok0 + rg * 32 + lq) * 1024 + h * 128 + m * 64 + hi * 32);
;     const uint4 q0 = qp[0], q1 = qp[1];
;     qf8[0] = q0.x; qf8[1] = q0.y; qf8[2] = q0.z; qf8[3] = q0.w; qf8[4] = q1.x; qf8[5] = q1.y; qf8[6] = q1.z; qf8[7] = q1.w;
;   }
;   float q2 = 0.f;
; #pragma unroll
;   for (int w = 0; w < 8; ++w) {
;     const float v0 = __builtin_amdgcn_cvt_f32_fp8(qf8[w], 0), v1 = __builtin_amdgcn_cvt_f32_fp8(qf8[w], 1);
;     const float v2 = __builtin_amdgcn_cvt_f32_fp8(qf8[w], 2), v3 = __builtin_amdgcn_cvt_f32_fp8(qf8[w], 3);
;     q2 += v0 * v0 + v1 * v1 + v2 * v2 + v3 * v3;
;   }
;   q2 = xhalf_sum(q2);
;   const float kmx2 = ((const float*)(p.ws + OFF_KMAX))[(b * 8 + h) * 2 + m];
;   const float sinit = -(sqrtf(q2 * kmx2) * 1.09f + 0.125f);
;   f32x16 oacc[4];
; #pragma unroll
;   for (int e = 0; e < 4; ++e)
; #pragma unroll
;     for (int i = 0; i < 16; ++i) oacc[e][i] = 0.f;
;   float lsum = 0.f;
.LBB0_202:
	s_and_b32 s0, s21, 7
	s_lshl_b32 s22, s0, 8
	s_ashr_i32 s0, s83, 8
	s_abs_i32 s5, s0
	s_mul_hi_u32 s8, s5, s82
	s_mul_i32 s9, s8, s56
	s_sub_i32 s5, s5, s9
	s_and_b32 s59, s83, 7
	s_bfe_u32 s1, s83, 0x50003
	s_ashr_i32 s4, s83, 31
	s_add_i32 s9, s8, 1
	s_sub_i32 s23, s5, s56
	s_cmp_ge_u32 s5, s56
	s_cselect_b32 s8, s9, s8
	s_cselect_b32 s5, s23, s5
	s_add_i32 s9, s8, 1
	s_cmp_ge_u32 s5, s56
	s_cselect_b32 s5, s9, s8
	s_xor_b32 s5, s5, s4
	s_sub_i32 s4, s5, s4
	s_mul_i32 s5, s4, s56
	s_sub_i32 s0, s0, s5
	s_lshl_b32 s0, s0, 5
	v_mov_b32_e32 v8, v162
	s_or_b32 s84, s0, s1
	s_ashr_i32 s5, s4, 31
	v_readfirstlane_b32 s0, v8
	s_ashr_i32 s68, s0, 6
	s_lshl_b64 vcc, s[4:5], s57
	s_and_b32 s1, s68, 3
	s_ashr_i32 s58, s0, 8
	s_lshl_b64 s[24:25], vcc, 10
	s_lshl_b32 s96, s59, 7
	s_lshl_b64 s[8:9], vcc, 11
	s_add_u32 s69, s74, s8
	s_addc_u32 s80, s75, s9
	s_ashr_i32 s85, s84, 31
	s_lshl_b64 s[84:85], s[84:85], 7
	v_and_b32_e32 v9, 31, v8
	s_add_u32 s5, s84, vcc_lo
	s_addc_u32 s23, s85, vcc_hi
	v_or_b32_e32 v0, s5, v9
	v_lshl_or_b32 v0, s1, 5, v0
	v_mov_b32_e32 v1, s23
	v_readlane_b32 s12, v254, 12
	v_lshlrev_b64 v[154:155], 10, v[0:1]
	v_readlane_b32 s13, v254, 13
	s_lshl_b32 s84, s58, 6
	s_ashr_i32 s85, s84, 31
	v_lshl_add_u64 v[0:1], s[12:13], 0, v[154:155]
	v_lshl_add_u64 v[0:1], v[0:1], 0, s[96:97]
	v_lshl_add_u64 v[0:1], v[0:1], 0, s[84:85]
	v_and_b32_e32 v152, 32, v8
	v_lshl_add_u64 v[0:1], v[0:1], 0, v[152:153]
	global_load_dwordx4 v[144:147], v[0:1], off
	global_load_dwordx4 v[148:151], v[0:1], off offset:16
	s_add_u32 s5, s30, s24
	s_addc_u32 s23, s31, s25
	s_add_u32 s24, s5, s96
	s_addc_u32 s25, s23, 0
	s_lshl_b32 s4, s4, 4
	s_lshl_b32 s5, s59, 1
	s_or_b32 s4, s4, s5
	s_add_i32 s4, s4, s58
	s_ashr_i32 s5, s4, 31
	s_lshl_b64 s[4:5], s[4:5], 2
	v_readlane_b32 s12, v254, 20
	v_readlane_b32 s13, v254, 21
	s_add_u32 s4, s12, s4
	s_addc_u32 s5, s13, s5
	global_load_dword v10, v153, s[4:5]
	s_mov_b32 s4, 0xf800000
	s_mov_b64 s[12:13], 0x10000
	s_barrier
	v_bfe_u32 v152, v8, 5, 1
	v_and_b32_e32 v182, 63, v8
	v_mov_b32_e32 v188, 0
	s_mov_b32 s23, 5
	s_mov_b32 s84, 0x18000
	v_mov_b32_e32 v48, 0
	v_mov_b32_e32 v49, v188
	v_mov_b32_e32 v50, v188
	v_mov_b32_e32 v51, v188
	v_mov_b32_e32 v52, v188
	v_mov_b32_e32 v53, v188
	v_mov_b32_e32 v54, v188
	v_mov_b32_e32 v55, v188
	v_mov_b32_e32 v56, v188
	v_mov_b32_e32 v57, v188
	v_mov_b32_e32 v58, v188
	v_mov_b32_e32 v59, v188
	v_mov_b32_e32 v60, v188
	v_mov_b32_e32 v61, v188
	v_mov_b32_e32 v62, v188
	v_mov_b32_e32 v63, v188
	v_mov_b32_e32 v32, 0
	v_mov_b32_e32 v33, v188
	v_mov_b32_e32 v34, v188
	v_mov_b32_e32 v35, v188
	v_mov_b32_e32 v36, v188
	v_mov_b32_e32 v37, v188
	v_mov_b32_e32 v38, v188
	v_mov_b32_e32 v39, v188
	v_mov_b32_e32 v40, v188
	v_mov_b32_e32 v41, v188
	v_mov_b32_e32 v42, v188
	v_mov_b32_e32 v43, v188
	v_mov_b32_e32 v44, v188
	v_mov_b32_e32 v45, v188
	v_mov_b32_e32 v46, v188
	v_mov_b32_e32 v47, v188
	v_mov_b32_e32 v27, v188
	v_mov_b32_e32 v28, v188
	v_mov_b32_e32 v29, v188
	v_mov_b32_e32 v30, v188
	v_mov_b32_e32 v31, v188
	s_waitcnt vmcnt(2)
	v_cvt_f32_fp8_sdwa v1, v144 src0_sel:BYTE_1
	v_cvt_f32_fp8_sdwa v5, v145 src0_sel:BYTE_1
	v_cvt_f32_fp8_e32 v0, v144
	v_cvt_f32_fp8_e32 v4, v145
	v_cvt_f32_fp8_sdwa v12, v146 src0_sel:BYTE_1
	v_cvt_f32_fp8_sdwa v2, v144 src0_sel:BYTE_2
	v_cvt_f32_fp8_sdwa v6, v145 src0_sel:BYTE_2
	v_cvt_f32_fp8_e32 v11, v146
	v_cvt_f32_fp8_sdwa v16, v147 src0_sel:BYTE_1
	v_cvt_f32_fp8_sdwa v3, v144 src0_sel:BYTE_3
	v_cvt_f32_fp8_sdwa v7, v145 src0_sel:BYTE_3
	v_cvt_f32_fp8_sdwa v13, v146 src0_sel:BYTE_2
	v_cvt_f32_fp8_e32 v15, v147
	s_waitcnt vmcnt(1)
	v_cvt_f32_fp8_sdwa v20, v148 src0_sel:BYTE_1
	v_cvt_f32_fp8_sdwa v14, v146 src0_sel:BYTE_3
	v_cvt_f32_fp8_sdwa v17, v147 src0_sel:BYTE_2
	v_cvt_f32_fp8_e32 v19, v148
	v_cvt_f32_fp8_sdwa v24, v149 src0_sel:BYTE_1
	v_mul_f32_e32 v1, v1, v1
	v_mul_f32_e32 v5, v5, v5
	v_cvt_f32_fp8_sdwa v18, v147 src0_sel:BYTE_3
	v_cvt_f32_fp8_sdwa v21, v148 src0_sel:BYTE_2
	v_cvt_f32_fp8_e32 v23, v149
	v_mul_f32_e32 v12, v12, v12
	v_fmac_f32_e32 v1, v0, v0
	v_fmac_f32_e32 v5, v4, v4
	v_cvt_f32_fp8_sdwa v22, v148 src0_sel:BYTE_3
	v_cvt_f32_fp8_sdwa v25, v149 src0_sel:BYTE_2
	v_mul_f32_e32 v16, v16, v16
	v_fmac_f32_e32 v12, v11, v11
	v_fmac_f32_e32 v1, v2, v2
	v_fmac_f32_e32 v5, v6, v6
	v_cvt_f32_fp8_sdwa v26, v149 src0_sel:BYTE_3
	v_mul_f32_e32 v20, v20, v20
	v_fmac_f32_e32 v16, v15, v15
	v_fmac_f32_e32 v12, v13, v13
	v_fmac_f32_e32 v1, v3, v3
	v_fmac_f32_e32 v5, v7, v7
	v_mul_f32_e32 v24, v24, v24
	v_fmac_f32_e32 v20, v19, v19
	v_fmac_f32_e32 v16, v17, v17
	v_fmac_f32_e32 v12, v14, v14
	v_add_f32_e32 v0, v1, v5
	v_fmac_f32_e32 v24, v23, v23
	v_fmac_f32_e32 v20, v21, v21
	v_fmac_f32_e32 v16, v18, v18
	v_add_f32_e32 v0, v0, v12
	v_fmac_f32_e32 v24, v25, v25
	v_fmac_f32_e32 v20, v22, v22
	v_add_f32_e32 v0, v0, v16
	v_fmac_f32_e32 v24, v26, v26
	v_add_f32_e32 v0, v0, v20
	v_cvt_f32_fp8_sdwa v2, v150 src0_sel:BYTE_1
	v_cvt_f32_fp8_sdwa v3, v151 src0_sel:BYTE_1
	v_add_f32_e32 v11, v0, v24
	v_cvt_f32_fp8_e32 v0, v150
	v_cvt_f32_fp8_e32 v1, v151
	v_cvt_f32_fp8_sdwa v4, v150 src0_sel:BYTE_2
	v_cvt_f32_fp8_sdwa v5, v151 src0_sel:BYTE_2
	v_cvt_f32_fp8_sdwa v6, v150 src0_sel:BYTE_3
	v_cvt_f32_fp8_sdwa v7, v151 src0_sel:BYTE_3
	v_pk_mul_f32 v[2:3], v[2:3], v[2:3]
	v_bfe_u32 v13, v8, 2, 2
	v_pk_fma_f32 v[0:1], v[0:1], v[0:1], v[2:3]
	v_bfe_u32 v16, v8, 1, 1
	v_pk_fma_f32 v[0:1], v[4:5], v[4:5], v[0:1]
	v_lshlrev_b32_e32 v14, 10, v152
	v_pk_fma_f32 v[0:1], v[6:7], v[6:7], v[0:1]
	v_lshlrev_b32_e32 v15, 8, v13
	v_add_f32_e32 v0, v11, v0
	v_add_f32_e32 v0, v0, v1
	v_mov_b32_e32 v1, v0
	s_nop 1
	v_permlane32_swap_b32_e32 v0, v1
	v_add_f32_e32 v0, v0, v1
	s_waitcnt vmcnt(0)
; #define LDS3 __attribute__((address_space(3)))
; #define RAW_BARRIER() do { asm volatile("s_waitcnt lgkmcnt(0)" ::: "memory"); __builtin_amdgcn_s_barrier(); } while (0)
; DI void attn_item(const Params& p, int L, int b, int h, int qb, float lam, char* lds) {
;     ...
;   const float sinit = -(sqrtf(q2 * kmx2) * 1.09f + 0.125f);
;   f32x16 oacc[4];
; #pragma unroll
;   for (int e = 0; e < 4; ++e)
; #pragma unroll
;     for (int i = 0; i < 16; ++i) oacc[e][i] = 0.f;
;   float lsum = 0.f;
;   const int nkt = L / 64;
;   const int krow = wave * 8 + (lane >> 3);
;   const int gk = krow * 1024 + (((lane & 7) ^ ((krow >> 1) & 7)) * 16);
;   const int drow = wave * 8 + (lane >> 4), dcp = lane & 15;
;   const int gv0 = drow * 1024 + ((dcp ^ ((drow & 3) << 2)) * 8), gv1 = (drow + 4) * 1024 + ((dcp ^ (((drow + 4) & 3) << 2)) * 8);
;   auto dma_tile = [&](int j) {
;     char* st = lds + (j & 3) * A_STAGE;
;     const unsigned char* kt = kg8 + (size_t)min(j + 1, nkt - 1) * 64 * 1024;
;     const bf16_t* vt = vg + (size_t)j * 64 * 1024;
;     __builtin_amdgcn_global_load_lds((const unsigned*)(kt + gk), (LDS3 unsigned*)(st + wave * 1024), 16, 0, 0);
;     __builtin_amdgcn_global_load_lds((const unsigned*)(vt + gv0), (LDS3 unsigned*)(st + A_KB + wave * 8 * 256), 16, 0, 0);
;     __builtin_amdgcn_global_load_lds((const unsigned*)(vt + gv1), (LDS3 unsigned*)(st + A_KB + wave * 8 * 256 + 4 * 256), 16, 0, 0);
;   };
;   __syncthreads();
;   __builtin_amdgcn_global_load_lds((const unsigned*)(kg8 + gk), (LDS3 unsigned*)(lds + 3 * A_STAGE + wave * 1024), 16, 0, 0);
;   dma_tile(0); dma_tile(1); dma_tile(2);
;   LDS3 char* const l3 = (LDS3 char*)lds;
;   int vro[4];
;   const int kro = lq * 128 + (((m * 4 + hi * 2) ^ ((lq >> 1) & 7)) * 16);
;   {
;     const int tq = (lane & 15) >> 2, tp = lane & 3, blk = (lane >> 4) & 1;
; #pragma unroll
;     for (int eb = 0; eb < 4; ++eb) vro[eb] = A_KB + (4 * hi + tq) * 256 + ((((eb ^ tq) * 4) + blk * 2 + (tp >> 1)) * 16) + (tp & 1) * 8;
;   }
;     ...
;   const unsigned lds_addr0 = (unsigned)(size_t)lds;
;     ...
;   f32x16 sA0, sA1, sB0, sB1;
;   f32x16 sv;
; #pragma unroll
;   for (int i = 0; i < 16; ++i) sv[i] = sinit;
;     ...
;   asm volatile("s_waitcnt vmcnt(0)" ::: "memory");
;   RAW_BARRIER();
;   {
;     v8i_t k0, k1;
;     LDK8(k0, 3 * A_STAGE + kro) LDK8(k1, 3 * A_STAGE + kro + 32 * 128)
;     sA0 = QK8(k0, sv); sA1 = QK8(k1, sv);
;   }
	v_mul_f32_e32 v0, v10, v0
	v_mul_f32_e32 v1, 0x4f800000, v0
	v_cmp_gt_f32_e32 vcc, s4, v0
	v_bfe_u32 v10, v8, 3, 3
	v_bfe_u32 v11, v8, 4, 2
	v_cndmask_b32_e32 v0, v0, v1, vcc
	v_sqrt_f32_e32 v1, v0
	v_mov_b32_e32 v17, v188
	v_mov_b32_e32 v18, v188
	v_mov_b32_e32 v19, v188
	v_add_u32_e32 v2, -1, v1
	v_fma_f32 v3, -v2, v1, v0
	v_cmp_ge_f32_e64 s[4:5], 0, v3
	v_add_u32_e32 v3, 1, v1
	v_mov_b32_e32 v20, v188
	v_cndmask_b32_e64 v2, v1, v2, s[4:5]
	v_fma_f32 v1, -v3, v1, v0
	v_cmp_lt_f32_e64 s[4:5], 0, v1
	v_mov_b32_e32 v21, v188
	v_mov_b32_e32 v22, v188
	v_cndmask_b32_e64 v1, v2, v3, s[4:5]
	v_mul_f32_e32 v2, 0x37800000, v1
	s_lshl_b32 s4, s59, 8
	v_cndmask_b32_e32 v1, v1, v2, vcc
	v_cmp_class_f32_e32 vcc, v0, v164
	s_add_u32 s4, s69, s4
	s_addc_u32 s5, s80, 0
	v_cndmask_b32_e32 v0, v1, v0, vcc
	s_lshl_b32 s59, s68, 3
	v_fmamk_f32 v6, v0, 0x3f8b851f, v165
	v_or_b32_e32 v0, s59, v10
	v_lshlrev_b32_e32 v1, 10, v0
	v_lshrrev_b32_e32 v0, 1, v0
	v_xor_b32_e32 v0, v0, v8
	v_lshlrev_b32_e32 v0, 4, v0
	s_movk_i32 s69, 0x70
	v_and_or_b32 v0, v0, s69, v1
	v_or_b32_e32 v1, s59, v11
	v_and_b32_e32 v2, 15, v8
	v_lshlrev_b32_e32 v1, 10, v1
	v_lshlrev_b32_e32 v3, 5, v11
	v_lshlrev_b32_e32 v2, 3, v2
	v_xor_b32_e32 v12, v3, v2
	v_bitop3_b32 v2, v1, v3, v2 bitop3:0xf6
	v_ashrrev_i32_e32 v1, 31, v0
	s_lshl_b32 s59, s68, 10
	v_lshl_add_u64 v[156:157], s[24:25], 0, v[0:1]
	s_add_i32 m0, s59, 0x18000
	v_lshl_add_u64 v[0:1], v[156:157], 0, s[12:13]
	global_load_lds_dwordx4 v[156:157], off
	s_mov_b32 m0, s59
	v_ashrrev_i32_e32 v3, 31, v2
	v_or_b32_e32 v4, 0x1000, v2
	global_load_lds_dwordx4 v[0:1], off
	v_lshlrev_b64 v[0:1], 1, v[2:3]
	s_add_i32 s69, s59, s59
	v_lshl_add_u64 v[2:3], s[4:5], 0, v[0:1]
	s_add_i32 m0, s69, 0x4000
	v_ashrrev_i32_e32 v5, 31, v4
	s_lshl_b32 s85, s68, 11
	global_load_lds_dwordx4 v[2:3], off
	v_lshlrev_b64 v[2:3], 1, v[4:5]
	s_add_i32 m0, s69, 0x4400
	v_lshl_add_u64 v[4:5], s[4:5], 0, v[2:3]
	s_add_u32 s24, s4, 0x20000
	global_load_lds_dwordx4 v[4:5], off
	s_addc_u32 s25, s5, 0
	v_lshl_add_u64 v[4:5], v[156:157], 0, s[44:45]
	s_add_i32 m0, s59, 0x8000
	s_mov_b64 s[12:13], 0x30000
	global_load_lds_dwordx4 v[4:5], off
	v_lshl_add_u64 v[4:5], s[24:25], 0, v[0:1]
	s_add_i32 m0, s69, 0xc000
	v_xor_b32_e32 v64, 0x80000000, v6
	global_load_lds_dwordx4 v[4:5], off
	s_add_i32 m0, s69, 0xc400
	v_lshl_add_u64 v[4:5], s[24:25], 0, v[2:3]
	s_add_u32 s4, s4, 0x40000
	global_load_lds_dwordx4 v[4:5], off
	s_addc_u32 s5, s5, 0
	v_lshl_add_u64 v[4:5], v[156:157], 0, s[12:13]
	s_add_i32 m0, s59, 0x10000
	v_lshl_add_u64 v[0:1], s[4:5], 0, v[0:1]
	global_load_lds_dwordx4 v[4:5], off
	s_add_i32 m0, s85, 0x14000
	v_mov_b32_e32 v65, v64
	global_load_lds_dwordx4 v[0:1], off
	v_lshl_add_u64 v[0:1], s[4:5], 0, v[2:3]
	s_add_i32 m0, s85, 0x14400
	s_lshl_b32 s4, s58, 2
	global_load_lds_dwordx4 v[0:1], off
	v_lshlrev_b32_e32 v0, 1, v152
	v_bfe_u32 v1, v8, 1, 3
	v_bitop3_b32 v0, s4, v1, v0 bitop3:0x36
	v_lshlrev_b32_e32 v1, 7, v9
	v_lshl_add_u32 v183, v0, 4, v1
	v_add_u32_e32 v0, 0x18000, v183
	s_waitcnt vmcnt(9)
	v_xor_b32_e32 v4, 16, v0
	s_waitcnt lgkmcnt(0)
	s_barrier
	ds_read_b128 v[0:3], v0
	ds_read_b128 v[4:7], v4
	v_mov_b32_e32 v66, v64
	v_mov_b32_e32 v67, v64
	v_mov_b32_e32 v68, v64
	v_mov_b32_e32 v69, v64
	v_mov_b32_e32 v70, v64
	v_mov_b32_e32 v71, v64
	v_mov_b32_e32 v72, v64
	v_mov_b32_e32 v73, v64
	v_mov_b32_e32 v74, v64
	v_mov_b32_e32 v75, v64
	v_mov_b32_e32 v76, v64
	v_mov_b32_e32 v77, v64
	v_mov_b32_e32 v78, v64
	v_mov_b32_e32 v79, v64
	v_and_or_b32 v9, v10, 2, v16
	v_lshlrev_b32_e32 v10, 6, v13
	s_waitcnt lgkmcnt(0)
	v_mfma_scale_f32_32x32x64_f8f6f4 v[96:111], v[0:7], v[144:151], v[64:79], v166, v166 op_sel_hi:[0,0,0]
	v_lshlrev_b32_e32 v0, 3, v8
	v_and_b32_e32 v8, 8, v0
	v_add_u32_e32 v0, 0x19000, v183
	v_xor_b32_e32 v4, 16, v0
	ds_read_b128 v[0:3], v0
	ds_read_b128 v[4:7], v4
	v_or3_b32 v8, v15, v8, v14
	v_lshl_or_b32 v9, v9, 4, v10
	s_movk_i32 s4, 0x4040
	v_bitop3_b32 v185, v9, s4, v8 bitop3:0x36
	s_movk_i32 s4, 0x4080
	v_bitop3_b32 v186, v9, s4, v8 bitop3:0x36
	s_movk_i32 s4, 0x40c0
	v_bitop3_b32 v187, v9, s4, v8 bitop3:0x36
	s_lshl_b32 s4, s68, 13
	v_or_b32_e32 v10, v9, v8
	s_waitcnt lgkmcnt(0)
	v_mfma_scale_f32_32x32x64_f8f6f4 v[80:95], v[0:7], v[144:151], v[64:79], v166, v166 op_sel_hi:[0,0,0]
	v_lshlrev_b32_e32 v0, 10, v11
	v_or3_b32 v0, v12, s4, v0
	v_ashrrev_i32_e32 v1, 31, v0
	v_lshlrev_b64 v[158:159], 1, v[0:1]
	s_or_b32 s4, s8, s22
	v_or_b32_e32 v0, 0x1000, v0
	s_add_u32 s4, s10, s4
	v_ashrrev_i32_e32 v1, 31, v0
	v_or_b32_e32 v184, 0x4000, v10
	s_addc_u32 s5, s11, s9
	v_lshlrev_b64 v[160:161], 1, v[0:1]
	v_mov_b32_e32 v16, 0
	v_mov_b32_e32 v23, v188
	v_mov_b32_e32 v24, v188
	v_mov_b32_e32 v25, v188
	v_mov_b32_e32 v26, v188
	v_mov_b32_e32 v0, 0
	v_mov_b32_e32 v1, v188
	v_mov_b32_e32 v2, v188
	v_mov_b32_e32 v3, v188
	v_mov_b32_e32 v4, v188
	v_mov_b32_e32 v5, v188
	v_mov_b32_e32 v6, v188
	v_mov_b32_e32 v7, v188
	v_mov_b32_e32 v8, v188
	v_mov_b32_e32 v9, v188
	v_mov_b32_e32 v10, v188
	v_mov_b32_e32 v11, v188
	v_mov_b32_e32 v12, v188
	v_mov_b32_e32 v13, v188
	v_mov_b32_e32 v14, v188
	v_mov_b32_e32 v15, v188
	v_mov_b32_e32 v238, 0
	v_mov_b32_e32 v239, 0
	v_mov_b32_e32 v240, 0
	v_mov_b32_e32 v241, 0
	v_mov_b32_e32 v242, 0
	v_mov_b32_e32 v243, 0
	v_mov_b32_e32 v244, 0
	v_mov_b32_e32 v245, 0
	v_mov_b32_e32 v246, 0
	v_mov_b32_e32 v247, 0
	v_mov_b32_e32 v248, 0
	v_mov_b32_e32 v249, 0
	v_mov_b32_e32 v250, 0
	v_mov_b32_e32 v251, 0
	v_mov_b32_e32 v252, 0
	v_mov_b32_e32 v253, 0
	v_mov_b32_e32 v132, 0
	v_mov_b32_e32 v133, 0
	v_mov_b32_e32 v134, 0
	v_mov_b32_e32 v135, 0
	v_mov_b32_e32 v189, 0
	s_mov_b32 s23, 0
	s_mov_b32 s84, 0
	s_mov_b32 s25, 0
	s_mov_b32 s9, 0
	s_mov_b32 s68, 0x10000
	s_add_i32 s69, s68, s85
	s_add_i32 s22, s68, s59
	s_add_u32 s80, s4, s86
	s_addc_u32 s81, s5, s87
	s_mov_b32 s4, s80
	s_mov_b32 s5, s81
	s_sub_u32 s80, s80, 0x20000
	s_subb_u32 s81, s81, 0
	s_mov_b32 s24, 0x30000
	s_lshl_b32 s12, s77, 16
	s_mov_b32 s8, 0x40000
	s_min_u32 s8, s8, s12
	s_add_i32 s13, s76, -2
	s_cmp_eq_u32 s58, 1
	s_cbranch_scc0 .Lat_noprio
	s_setprio 1
